# P5: residual x loads marked nt (read once, keep GEMM operands cached) on top of sc1 write-through out stores
# speedup vs baseline: 1.0181x; 1.0110x over previous
.LBB0_2586:
	s_ashr_i32 s14, s87, 3
	s_and_b32 s14, s14, -4
	s_and_b32 s15, s87, 3
	s_add_i32 s14, s14, s39
	s_or_b32 s15, s14, s15
	v_readfirstlane_b32 s20, v128
	s_lshl_b32 s24, s15, 8
	s_lshr_b32 s15, s20, 1
	s_lshl_b32 s19, s87, 5
	s_and_b32 s15, s15, 0x7fffffc0
	s_and_b32 s19, s19, 0x380
	s_add_i32 s21, s15, s24
	s_and_b32 s13, s2, 3
	s_and_b32 s12, s3, 0x380
	s_lshr_b32 s25, s20, 6
	v_or_b32_e32 v0, s21, v134
	s_and_b32 s20, s20, 64
	s_lshl_b32 s21, s19, 2
	s_waitcnt lgkmcnt(0)
	s_add_u32 s21, s0, s21
	s_addc_u32 s23, s1, 0
	s_lshl_b32 s22, s20, 2
	s_add_u32 s22, s21, s22
	s_addc_u32 s23, s23, 0
	v_ashrrev_i32_e32 v1, 31, v0
	v_or_b32_e32 v6, 1, v0
	v_or_b32_e32 v8, 2, v0
	v_or_b32_e32 v10, 3, v0
	v_lshl_add_u64 v[2:3], s[22:23], 0, v[76:77]
	v_lshlrev_b64 v[78:79], 12, v[0:1]
	v_ashrrev_i32_e32 v7, 31, v6
	v_ashrrev_i32_e32 v9, 31, v8
	v_ashrrev_i32_e32 v11, 31, v10
	v_lshl_add_u64 v[4:5], v[2:3], 0, v[78:79]
	v_lshlrev_b64 v[80:81], 12, v[6:7]
	v_lshlrev_b64 v[82:83], 12, v[8:9]
	v_lshlrev_b64 v[84:85], 12, v[10:11]
	v_lshl_add_u64 v[6:7], v[2:3], 0, v[80:81]
	v_lshl_add_u64 v[8:9], v[2:3], 0, v[82:83]
	v_lshl_add_u64 v[10:11], v[2:3], 0, v[84:85]
	global_load_dword v168, v[4:5], off nt
	global_load_dword v167, v[4:5], off offset:128 nt
	global_load_dword v166, v[6:7], off nt
	global_load_dword v165, v[6:7], off offset:128 nt
	global_load_dword v164, v[8:9], off nt
	global_load_dword v163, v[8:9], off offset:128 nt
	global_load_dword v162, v[10:11], off nt
	global_load_dword v135, v[10:11], off offset:128 nt
	v_or_b32_e32 v4, 8, v0
	v_ashrrev_i32_e32 v5, 31, v4
	v_or_b32_e32 v6, 9, v0
	v_or_b32_e32 v8, 10, v0
	v_or_b32_e32 v10, 11, v0
	v_lshlrev_b64 v[86:87], 12, v[4:5]
	v_ashrrev_i32_e32 v7, 31, v6
	v_ashrrev_i32_e32 v9, 31, v8
	v_ashrrev_i32_e32 v11, 31, v10
	v_lshl_add_u64 v[4:5], v[2:3], 0, v[86:87]
	v_lshlrev_b64 v[88:89], 12, v[6:7]
	v_lshlrev_b64 v[90:91], 12, v[8:9]
	v_lshlrev_b64 v[92:93], 12, v[10:11]
	v_lshl_add_u64 v[6:7], v[2:3], 0, v[88:89]
	v_lshl_add_u64 v[8:9], v[2:3], 0, v[90:91]
	v_lshl_add_u64 v[10:11], v[2:3], 0, v[92:93]
	global_load_dword v176, v[4:5], off nt
	global_load_dword v175, v[4:5], off offset:128 nt
	global_load_dword v174, v[6:7], off nt
	global_load_dword v173, v[6:7], off offset:128 nt
	global_load_dword v172, v[8:9], off nt
	global_load_dword v171, v[8:9], off offset:128 nt
	global_load_dword v170, v[10:11], off nt
	global_load_dword v169, v[10:11], off offset:128 nt
	v_or_b32_e32 v4, 16, v0
	v_ashrrev_i32_e32 v5, 31, v4
	v_or_b32_e32 v6, 17, v0
	v_or_b32_e32 v8, 18, v0
	v_or_b32_e32 v10, 19, v0
	v_lshlrev_b64 v[94:95], 12, v[4:5]
	v_ashrrev_i32_e32 v7, 31, v6
	v_ashrrev_i32_e32 v9, 31, v8
	v_ashrrev_i32_e32 v11, 31, v10
	v_lshl_add_u64 v[4:5], v[2:3], 0, v[94:95]
	v_lshlrev_b64 v[96:97], 12, v[6:7]
	v_lshlrev_b64 v[98:99], 12, v[8:9]
	v_lshlrev_b64 v[100:101], 12, v[10:11]
	v_lshl_add_u64 v[6:7], v[2:3], 0, v[96:97]
	v_lshl_add_u64 v[8:9], v[2:3], 0, v[98:99]
	v_lshl_add_u64 v[10:11], v[2:3], 0, v[100:101]
	global_load_dword v184, v[4:5], off nt
	global_load_dword v183, v[4:5], off offset:128 nt
	global_load_dword v182, v[6:7], off nt
	global_load_dword v181, v[6:7], off offset:128 nt
	global_load_dword v180, v[8:9], off nt
	global_load_dword v179, v[8:9], off offset:128 nt
	global_load_dword v178, v[10:11], off nt
	global_load_dword v177, v[10:11], off offset:128 nt
	v_or_b32_e32 v4, 24, v0
	v_ashrrev_i32_e32 v5, 31, v4
	v_or_b32_e32 v6, 25, v0
	v_or_b32_e32 v8, 26, v0
	v_or_b32_e32 v10, 27, v0
	v_lshlrev_b64 v[102:103], 12, v[4:5]
	v_ashrrev_i32_e32 v7, 31, v6
	v_ashrrev_i32_e32 v9, 31, v8
	v_ashrrev_i32_e32 v11, 31, v10
	v_lshl_add_u64 v[4:5], v[2:3], 0, v[102:103]
	v_lshlrev_b64 v[104:105], 12, v[6:7]
	v_lshlrev_b64 v[106:107], 12, v[8:9]
	v_lshlrev_b64 v[108:109], 12, v[10:11]
	v_lshl_add_u64 v[6:7], v[2:3], 0, v[104:105]
	v_lshl_add_u64 v[8:9], v[2:3], 0, v[106:107]
	v_lshl_add_u64 v[10:11], v[2:3], 0, v[108:109]
	global_load_dword v197, v[4:5], off nt
	global_load_dword v191, v[4:5], off offset:128 nt
	global_load_dword v190, v[6:7], off nt
	global_load_dword v189, v[6:7], off offset:128 nt
	global_load_dword v188, v[8:9], off nt
	global_load_dword v187, v[8:9], off offset:128 nt
	global_load_dword v186, v[10:11], off nt
	global_load_dword v185, v[10:11], off offset:128 nt
	v_or_b32_e32 v4, 32, v0
	v_ashrrev_i32_e32 v5, 31, v4
	v_or_b32_e32 v6, 33, v0
	v_or_b32_e32 v8, 34, v0
	v_or_b32_e32 v10, 35, v0
	v_lshlrev_b64 v[110:111], 12, v[4:5]
	v_ashrrev_i32_e32 v7, 31, v6
	v_ashrrev_i32_e32 v9, 31, v8
	v_ashrrev_i32_e32 v11, 31, v10
	v_lshl_add_u64 v[4:5], v[2:3], 0, v[110:111]
	v_lshlrev_b64 v[112:113], 12, v[6:7]
	v_lshlrev_b64 v[114:115], 12, v[8:9]
	v_lshlrev_b64 v[116:117], 12, v[10:11]
	v_lshl_add_u64 v[6:7], v[2:3], 0, v[112:113]
	v_lshl_add_u64 v[8:9], v[2:3], 0, v[114:115]
	v_lshl_add_u64 v[10:11], v[2:3], 0, v[116:117]
	global_load_dword v205, v[4:5], off nt
	global_load_dword v204, v[4:5], off offset:128 nt
	global_load_dword v203, v[6:7], off nt
	global_load_dword v202, v[6:7], off offset:128 nt
	global_load_dword v201, v[8:9], off nt
	global_load_dword v200, v[8:9], off offset:128 nt
	global_load_dword v199, v[10:11], off nt
	global_load_dword v198, v[10:11], off offset:128 nt
	v_or_b32_e32 v4, 40, v0
	v_ashrrev_i32_e32 v5, 31, v4
	v_or_b32_e32 v6, 41, v0
	v_or_b32_e32 v8, 42, v0
	v_or_b32_e32 v10, 43, v0
	v_lshlrev_b64 v[118:119], 12, v[4:5]
	v_ashrrev_i32_e32 v7, 31, v6
	v_ashrrev_i32_e32 v9, 31, v8
	v_ashrrev_i32_e32 v11, 31, v10
	v_lshl_add_u64 v[4:5], v[2:3], 0, v[118:119]
	v_lshlrev_b64 v[120:121], 12, v[6:7]
	v_lshlrev_b64 v[122:123], 12, v[8:9]
	v_lshlrev_b64 v[124:125], 12, v[10:11]
	v_lshl_add_u64 v[6:7], v[2:3], 0, v[120:121]
	v_lshl_add_u64 v[8:9], v[2:3], 0, v[122:123]
	v_lshl_add_u64 v[10:11], v[2:3], 0, v[124:125]
	global_load_dword v213, v[4:5], off nt
	global_load_dword v212, v[4:5], off offset:128 nt
	global_load_dword v211, v[6:7], off nt
	global_load_dword v210, v[6:7], off offset:128 nt
	global_load_dword v208, v[8:9], off nt
	global_load_dword v209, v[8:9], off offset:128 nt
	global_load_dword v207, v[10:11], off nt
	global_load_dword v206, v[10:11], off offset:128 nt
	v_or_b32_e32 v4, 48, v0
	v_ashrrev_i32_e32 v5, 31, v4
	v_or_b32_e32 v6, 49, v0
	v_or_b32_e32 v8, 50, v0
	v_or_b32_e32 v10, 51, v0
	v_lshlrev_b64 v[126:127], 12, v[4:5]
	v_ashrrev_i32_e32 v7, 31, v6
	v_ashrrev_i32_e32 v9, 31, v8
	v_ashrrev_i32_e32 v11, 31, v10
	v_lshl_add_u64 v[4:5], v[2:3], 0, v[126:127]
	v_lshlrev_b64 v[136:137], 12, v[6:7]
	v_lshlrev_b64 v[138:139], 12, v[8:9]
	v_lshlrev_b64 v[140:141], 12, v[10:11]
	v_lshl_add_u64 v[6:7], v[2:3], 0, v[136:137]
	v_lshl_add_u64 v[8:9], v[2:3], 0, v[138:139]
	v_lshl_add_u64 v[10:11], v[2:3], 0, v[140:141]
	global_load_dword v221, v[4:5], off nt
	global_load_dword v220, v[4:5], off offset:128 nt
	global_load_dword v219, v[6:7], off nt
	global_load_dword v218, v[6:7], off offset:128 nt
	global_load_dword v217, v[8:9], off nt
	global_load_dword v216, v[8:9], off offset:128 nt
	global_load_dword v215, v[10:11], off nt
	global_load_dword v214, v[10:11], off offset:128 nt
	v_or_b32_e32 v4, 56, v0
	v_ashrrev_i32_e32 v5, 31, v4
	v_or_b32_e32 v6, 57, v0
	v_or_b32_e32 v8, 58, v0
	v_or_b32_e32 v0, 59, v0
	v_lshlrev_b64 v[142:143], 12, v[4:5]
	v_ashrrev_i32_e32 v7, 31, v6
	v_ashrrev_i32_e32 v9, 31, v8
	v_ashrrev_i32_e32 v1, 31, v0
	s_lshl_b32 s27, s25, 5
	v_lshl_add_u64 v[4:5], v[2:3], 0, v[142:143]
	v_lshlrev_b64 v[144:145], 12, v[6:7]
	v_lshlrev_b64 v[146:147], 12, v[8:9]
	v_lshlrev_b64 v[148:149], 12, v[0:1]
	s_or_b32 s22, s27, 8
	v_lshl_add_u64 v[6:7], v[2:3], 0, v[144:145]
	v_lshl_add_u64 v[8:9], v[2:3], 0, v[146:147]
	v_lshl_add_u64 v[0:1], v[2:3], 0, v[148:149]
	global_load_dword v229, v[4:5], off nt
	global_load_dword v228, v[4:5], off offset:128 nt
	global_load_dword v227, v[6:7], off nt
	global_load_dword v226, v[6:7], off offset:128 nt
	global_load_dword v225, v[8:9], off nt
	global_load_dword v224, v[8:9], off offset:128 nt
	global_load_dword v223, v[0:1], off nt
	global_load_dword v222, v[0:1], off offset:128 nt
	v_or_b32_e32 v4, s24, v192
	v_or_b32_e32 v2, s22, v192
	v_add_u32_e32 v0, s27, v4
	v_lshrrev_b32_e32 v12, 1, v2
	v_add_u32_e32 v2, s24, v2
	s_or_b32 s26, s27, 24
	v_ashrrev_i32_e32 v1, 31, v0
	s_lshl_b32 s21, s25, 12
	v_xor_b32_e32 v5, v12, v128
	v_ashrrev_i32_e32 v3, 31, v2
	v_readlane_b32 s34, v254, 2
	s_or_b32 s23, s27, 16
	v_or_b32_e32 v6, s26, v192
	v_lshlrev_b64 v[0:1], 11, v[0:1]
	s_add_i32 s28, s21, 0
	v_lshlrev_b64 v[2:3], 11, v[2:3]
	v_readlane_b32 s35, v254, 3
	v_lshlrev_b32_e32 v5, 4, v5
	s_lshl_b32 s22, s22, 7
	v_add_u32_e32 v4, s23, v4
	v_lshrrev_b32_e32 v13, 1, v6
	v_add_u32_e32 v6, s24, v6
	v_lshl_add_u64 v[0:1], v[66:67], 0, v[0:1]
	s_mov_b32 m0, s28
	v_lshl_add_u64 v[2:3], s[34:35], 0, v[2:3]
	v_and_b32_e32 v64, 0x70, v5
	s_add_i32 s29, s22, 0
	v_ashrrev_i32_e32 v5, 31, v4
	s_lshl_b32 s23, s23, 7
	v_xor_b32_e32 v8, v13, v128
	v_ashrrev_i32_e32 v7, 31, v6
	s_waitcnt lgkmcnt(0)
	s_barrier
	global_load_lds_dwordx4 v[0:1], off
	v_lshl_add_u64 v[2:3], v[2:3], 0, v[64:65]
	s_mov_b32 m0, s29
	v_lshlrev_b64 v[4:5], 11, v[4:5]
	s_add_i32 s30, s23, 0
	v_lshlrev_b64 v[6:7], 11, v[6:7]
	v_lshlrev_b32_e32 v8, 4, v8
	s_lshl_b32 s24, s26, 7
	global_load_lds_dwordx4 v[2:3], off
	v_lshl_add_u64 v[4:5], v[66:67], 0, v[4:5]
	s_mov_b32 m0, s30
	v_lshl_add_u64 v[6:7], s[34:35], 0, v[6:7]
	v_and_b32_e32 v64, 0x70, v8
	s_add_i32 s31, s24, 0
	s_lshl_b32 s33, s25, 4
	s_lshl_b32 s25, s25, 11
	global_load_lds_dwordx4 v[4:5], off
	v_lshl_add_u64 v[6:7], v[6:7], 0, v[64:65]
	s_mov_b32 m0, s31
	s_add_i32 s26, s25, 0
	global_load_lds_dwordx4 v[6:7], off
	s_add_i32 m0, s26, 0x8000
	s_or_b32 s26, s33, 8
	v_or_b32_e32 v8, s19, v192
	v_or_b32_e32 v10, s26, v192
	v_add_u32_e32 v64, s33, v8
	v_lshrrev_b32_e32 v14, 1, v10
	v_lshlrev_b64 v[8:9], 11, v[64:65]
	v_xor_b32_e32 v15, v14, v128
	v_add_u32_e32 v64, s19, v10
	v_lshlrev_b64 v[10:11], 11, v[64:65]
	v_lshlrev_b32_e32 v15, 4, v15
	s_lshl_b32 s26, s26, 7
	v_lshl_add_u64 v[8:9], v[68:69], 0, v[8:9]
	v_lshl_add_u64 v[10:11], s[36:37], 0, v[10:11]
	v_and_b32_e32 v64, 0x70, v15
	s_add_i32 s34, s26, 0
	global_load_lds_dwordx4 v[8:9], off
	v_lshl_add_u64 v[10:11], v[10:11], 0, v[64:65]
	s_add_i32 m0, s34, 0x8000
	v_lshl_add_u64 v[0:1], v[0:1], 0, s[10:11]
	global_load_lds_dwordx4 v[10:11], off
	s_add_i32 m0, s28, 0xc000
	s_add_i32 s14, s14, s13
	global_load_lds_dwordx4 v[0:1], off
	v_lshl_add_u64 v[0:1], v[2:3], 0, s[10:11]
	s_add_i32 m0, s29, 0xc000
	s_lshl_b32 s13, s14, 8
	global_load_lds_dwordx4 v[0:1], off
	v_lshl_add_u64 v[0:1], v[4:5], 0, s[10:11]
	s_add_i32 m0, s30, 0xc000
	s_add_i32 s27, s27, s13
	global_load_lds_dwordx4 v[0:1], off
	v_lshl_add_u64 v[0:1], v[6:7], 0, s[10:11]
	s_add_i32 m0, s31, 0xc000
	v_bitop3_b32 v2, v12, 7, v128 bitop3:0x48
	global_load_lds_dwordx4 v[0:1], off
	v_lshl_add_u64 v[0:1], v[8:9], 0, s[10:11]
	s_add_i32 m0, s17, s25
	s_add_i32 s33, s33, s12
	global_load_lds_dwordx4 v[0:1], off
	v_lshl_add_u64 v[0:1], v[10:11], 0, s[10:11]
	s_add_i32 m0, s17, s26
	v_or_b32_e32 v64, s33, v192
	global_load_lds_dwordx4 v[0:1], off
	v_or_b32_e32 v0, s15, v132
	v_or_b32_e32 v1, s20, v132
	v_lshlrev_b32_e32 v75, 7, v0
	v_or_b32_e32 v0, s27, v192
	v_lshlrev_b32_e32 v230, 7, v1
	v_ashrrev_i32_e32 v1, 31, v0
	v_lshlrev_b64 v[0:1], 11, v[0:1]
	v_lshl_add_u64 v[150:151], v[70:71], 0, v[0:1]
	v_or_b32_e32 v0, s27, v129
	v_ashrrev_i32_e32 v1, 31, v0
	v_lshlrev_b64 v[0:1], 11, v[0:1]
	v_lshl_or_b32 v0, v2, 4, v0
	v_lshl_add_u64 v[152:153], s[6:7], 0, v[0:1]
	v_or_b32_e32 v0, s27, v131
	v_ashrrev_i32_e32 v1, 31, v0
	v_lshlrev_b64 v[0:1], 11, v[0:1]
	v_lshl_add_u64 v[154:155], v[70:71], 0, v[0:1]
	v_or_b32_e32 v0, s27, v133
	v_ashrrev_i32_e32 v1, 31, v0
	v_lshlrev_b64 v[0:1], 11, v[0:1]
	v_bitop3_b32 v2, v13, 7, v128 bitop3:0x48
	v_lshl_or_b32 v0, v2, 4, v0
	v_lshl_add_u64 v[156:157], s[6:7], 0, v[0:1]
	v_lshlrev_b64 v[0:1], 11, v[64:65]
	v_or_b32_e32 v64, s33, v129
	v_lshl_add_u64 v[158:159], v[72:73], 0, v[0:1]
	v_lshlrev_b64 v[0:1], 11, v[64:65]
	v_bitop3_b32 v2, v14, 7, v128 bitop3:0x48
	v_lshl_or_b32 v0, v2, 4, v0
	v_lshl_add_u64 v[160:161], s[8:9], 0, v[0:1]
	s_mov_b64 s[12:13], 0
	s_mov_b32 s27, 2
	v_mov_b32_e32 v0, 0
	v_mov_b32_e32 v1, v65
	v_mov_b32_e32 v2, v65
	v_mov_b32_e32 v3, v65
	v_mov_b32_e32 v4, v65
	v_mov_b32_e32 v5, v65
	v_mov_b32_e32 v6, v65
	v_mov_b32_e32 v7, v65
	v_mov_b32_e32 v8, v65
	v_mov_b32_e32 v9, v65
	v_mov_b32_e32 v10, v65
	v_mov_b32_e32 v11, v65
	v_mov_b32_e32 v12, v65
	v_mov_b32_e32 v13, v65
	v_mov_b32_e32 v14, v65
	v_mov_b32_e32 v15, v65
	v_mov_b32_e32 v16, 0
	v_mov_b32_e32 v17, v65
	v_mov_b32_e32 v18, v65
	v_mov_b32_e32 v19, v65
	v_mov_b32_e32 v20, v65
	v_mov_b32_e32 v21, v65
	v_mov_b32_e32 v22, v65
	v_mov_b32_e32 v23, v65
	v_mov_b32_e32 v24, v65
	v_mov_b32_e32 v25, v65
	v_mov_b32_e32 v26, v65
	v_mov_b32_e32 v27, v65
	v_mov_b32_e32 v28, v65
	v_mov_b32_e32 v29, v65
	v_mov_b32_e32 v30, v65
	v_mov_b32_e32 v31, v65
	v_mov_b32_e32 v32, 0
	v_mov_b32_e32 v33, v65
	v_mov_b32_e32 v34, v65
	v_mov_b32_e32 v35, v65
	v_mov_b32_e32 v36, v65
	v_mov_b32_e32 v37, v65
	v_mov_b32_e32 v38, v65
	v_mov_b32_e32 v39, v65
	v_mov_b32_e32 v40, v65
	v_mov_b32_e32 v41, v65
	v_mov_b32_e32 v42, v65
	v_mov_b32_e32 v43, v65
	v_mov_b32_e32 v44, v65
	v_mov_b32_e32 v45, v65
	v_mov_b32_e32 v46, v65
	v_mov_b32_e32 v47, v65
	v_mov_b32_e32 v48, 0
	v_mov_b32_e32 v49, v65
	v_mov_b32_e32 v50, v65
	v_mov_b32_e32 v51, v65
	v_mov_b32_e32 v52, v65
	v_mov_b32_e32 v53, v65
	v_mov_b32_e32 v54, v65
	v_mov_b32_e32 v55, v65
	v_mov_b32_e32 v56, v65
	v_mov_b32_e32 v57, v65
	v_mov_b32_e32 v58, v65
	v_mov_b32_e32 v59, v65
	v_mov_b32_e32 v60, v65
	v_mov_b32_e32 v61, v65
	v_mov_b32_e32 v62, v65
	v_mov_b32_e32 v63, v65
	s_branch .LBB0_2588
